# x-projection GEMM: first K-iteration of every unit peeled with C=0 first-touch MFMAs, the 128 accumulator-zeroing moves per unit removed
# baseline (speedup 1.0000x reference)
.LBB0_630:
	s_ashr_i32 s85, s84, 31
	s_lshl_b64 s[22:23], s[84:85], 20
	s_cmp_eq_u32 s52, 0
	v_mov_b64_e32 v[0:1], 0x3a0
	s_cselect_b32 s31, s14, s50
	v_cmp_lt_i64_e32 vcc, s[76:77], v[0:1]
	s_cselect_b32 s30, s15, s51
	s_cselect_b32 s38, s8, s14
	s_cselect_b32 s39, s9, s15
	s_add_u32 s76, s31, s22
	s_addc_u32 s77, s30, s23
	s_and_b64 s[22:23], vcc, exec
	s_cselect_b32 s30, s77, s89
	s_cselect_b32 s31, s76, s88
	s_ashr_i32 s83, s82, 31
	s_lshl_b64 s[22:23], s[82:83], 20
	s_add_u32 s86, s38, s22
	s_addc_u32 s87, s39, s23
	s_and_b64 s[22:23], vcc, exec
	s_cselect_b32 s38, s87, s91
	s_cselect_b32 s39, s86, s90
	s_add_u32 s88, s88, 0x80080
	s_addc_u32 s89, s89, 0
	s_add_u32 s41, s90, 0x100
	s_addc_u32 s42, s91, 0
	s_mov_b32 s43, -2
	s_add_u32 s22, s88, 0xfff80080
	s_addc_u32 s23, s89, -1
	s_add_i32 s44, 0, 0x10000
	s_cmp_eq_u32 s43, 28
	s_cselect_b32 s23, s30, s23
	s_cselect_b32 s22, s31, s22
	s_cselect_b32 s91, s38, s42
	s_cselect_b32 s90, s39, s41
	s_add_i32 s81, 0, 0x14000
	ds_read_b128 v[144:147], v222
	ds_read_b128 v[148:151], v222 offset:1024
	ds_read_b128 v[152:155], v222 offset:2048
	ds_read_b128 v[156:159], v222 offset:3072
	ds_read_b128 v[160:163], v223
	ds_read_b128 v[164:167], v223 offset:1024
	ds_read_b128 v[168:171], v223 offset:2048
	ds_read_b128 v[172:175], v223 offset:3072
	s_add_i32 m0, s57, 0xc000
	ds_read_b128 v[176:179], v143
	ds_read_b128 v[180:183], v143 offset:1024
	ds_read_b128 v[184:187], v143 offset:2048
	ds_read_b128 v[188:191], v143 offset:3072
	ds_read_b128 v[192:195], v143 offset:4096
	ds_read_b128 v[196:199], v143 offset:5120
	ds_read_b128 v[200:203], v143 offset:6144
	ds_read_b128 v[204:207], v143 offset:7168
	global_load_lds_dwordx4 v136, s[88:89]
	s_add_i32 m0, s57, 0xe000
	s_nop 0
	global_load_lds_dwordx4 v138, s[88:89]
	s_waitcnt vmcnt(8)
	s_waitcnt lgkmcnt(0)
	s_barrier
	v_mfma_f32_16x16x32_bf16 v[124:127], v[144:147], v[176:179], 0
	v_mfma_f32_16x16x32_bf16 v[120:123], v[152:155], v[176:179], 0
	v_mfma_f32_16x16x32_bf16 v[116:119], v[144:147], v[184:187], 0
	v_mfma_f32_16x16x32_bf16 v[112:115], v[152:155], v[184:187], 0
	v_mfma_f32_16x16x32_bf16 v[100:103], v[144:147], v[192:195], 0
	v_mfma_f32_16x16x32_bf16 v[96:99], v[152:155], v[192:195], 0
	v_mfma_f32_16x16x32_bf16 v[84:87], v[144:147], v[200:203], 0
	v_mfma_f32_16x16x32_bf16 v[80:83], v[152:155], v[200:203], 0
	v_mfma_f32_16x16x32_bf16 v[124:127], v[148:151], v[180:183], v[124:127]
	v_mfma_f32_16x16x32_bf16 v[120:123], v[156:159], v[180:183], v[120:123]
	v_mfma_f32_16x16x32_bf16 v[116:119], v[148:151], v[188:191], v[116:119]
	v_mfma_f32_16x16x32_bf16 v[112:115], v[156:159], v[188:191], v[112:115]
	v_mfma_f32_16x16x32_bf16 v[100:103], v[148:151], v[196:199], v[100:103]
	v_mfma_f32_16x16x32_bf16 v[96:99], v[156:159], v[196:199], v[96:99]
	v_mfma_f32_16x16x32_bf16 v[84:87], v[148:151], v[204:207], v[84:87]
	v_mfma_f32_16x16x32_bf16 v[80:83], v[156:159], v[204:207], v[80:83]
	v_mfma_f32_16x16x32_bf16 v[108:111], v[160:163], v[176:179], 0
	v_mfma_f32_16x16x32_bf16 v[104:107], v[168:171], v[176:179], 0
	v_mfma_f32_16x16x32_bf16 v[92:95], v[160:163], v[184:187], 0
	v_mfma_f32_16x16x32_bf16 v[88:91], v[168:171], v[184:187], 0
	v_mfma_f32_16x16x32_bf16 v[76:79], v[160:163], v[192:195], 0
	v_mfma_f32_16x16x32_bf16 v[72:75], v[168:171], v[192:195], 0
	v_mfma_f32_16x16x32_bf16 v[68:71], v[160:163], v[200:203], 0
	v_mfma_f32_16x16x32_bf16 v[64:67], v[168:171], v[200:203], 0
	v_mfma_f32_16x16x32_bf16 v[108:111], v[164:167], v[180:183], v[108:111]
	v_mfma_f32_16x16x32_bf16 v[104:107], v[172:175], v[180:183], v[104:107]
	v_mfma_f32_16x16x32_bf16 v[92:95], v[164:167], v[188:191], v[92:95]
	v_mfma_f32_16x16x32_bf16 v[88:91], v[172:175], v[188:191], v[88:91]
	v_mfma_f32_16x16x32_bf16 v[76:79], v[164:167], v[196:199], v[76:79]
	v_mfma_f32_16x16x32_bf16 v[72:75], v[172:175], v[196:199], v[72:75]
	v_mfma_f32_16x16x32_bf16 v[68:71], v[164:167], v[204:207], v[68:71]
	v_mfma_f32_16x16x32_bf16 v[64:67], v[172:175], v[204:207], v[64:67]
	s_barrier
	s_add_i32 s44, s44, s96
	s_mov_b32 m0, s44
	ds_read_b128 v[176:179], v143 offset:16384
	ds_read_b128 v[180:183], v143 offset:17408
	ds_read_b128 v[184:187], v143 offset:18432
	ds_read_b128 v[188:191], v143 offset:19456
	ds_read_b128 v[192:195], v143 offset:20480
	ds_read_b128 v[196:199], v143 offset:21504
	ds_read_b128 v[200:203], v143 offset:22528
	ds_read_b128 v[204:207], v143 offset:23552
	global_load_lds_dwordx4 v130, s[90:91]
	s_add_i32 m0, s44, 0x2000
	s_add_u32 s44, s90, 0x80000
	s_addc_u32 s45, s91, 0
	s_add_i32 s81, s81, s96
	global_load_lds_dwordx4 v134, s[90:91]
	s_mov_b32 m0, s81
	s_nop 0
	global_load_lds_dwordx4 v130, s[44:45]
	s_add_i32 m0, s81, 0x2000
	s_nop 0
	global_load_lds_dwordx4 v134, s[44:45]
	s_mov_b32 m0, s57
	s_nop 0
	global_load_lds_dwordx4 v128, s[22:23]
	s_mov_b32 m0, s97
	s_nop 0
	global_load_lds_dwordx4 v132, s[22:23]
	s_waitcnt vmcnt(8)
	s_waitcnt lgkmcnt(0)
	s_barrier
	v_mfma_f32_16x16x32_bf16 v[60:63], v[144:147], v[176:179], 0
	v_mfma_f32_16x16x32_bf16 v[56:59], v[152:155], v[176:179], 0
	v_mfma_f32_16x16x32_bf16 v[52:55], v[144:147], v[184:187], 0
	v_mfma_f32_16x16x32_bf16 v[48:51], v[152:155], v[184:187], 0
	v_mfma_f32_16x16x32_bf16 v[36:39], v[144:147], v[192:195], 0
	v_mfma_f32_16x16x32_bf16 v[32:35], v[152:155], v[192:195], 0
	v_mfma_f32_16x16x32_bf16 v[20:23], v[144:147], v[200:203], 0
	v_mfma_f32_16x16x32_bf16 v[16:19], v[152:155], v[200:203], 0
	v_mfma_f32_16x16x32_bf16 v[60:63], v[148:151], v[180:183], v[60:63]
	v_mfma_f32_16x16x32_bf16 v[56:59], v[156:159], v[180:183], v[56:59]
	v_mfma_f32_16x16x32_bf16 v[52:55], v[148:151], v[188:191], v[52:55]
	v_mfma_f32_16x16x32_bf16 v[48:51], v[156:159], v[188:191], v[48:51]
	v_mfma_f32_16x16x32_bf16 v[36:39], v[148:151], v[196:199], v[36:39]
	v_mfma_f32_16x16x32_bf16 v[32:35], v[156:159], v[196:199], v[32:35]
	v_mfma_f32_16x16x32_bf16 v[20:23], v[148:151], v[204:207], v[20:23]
	v_mfma_f32_16x16x32_bf16 v[16:19], v[156:159], v[204:207], v[16:19]
	v_mfma_f32_16x16x32_bf16 v[44:47], v[160:163], v[176:179], 0
	v_mfma_f32_16x16x32_bf16 v[40:43], v[168:171], v[176:179], 0
	v_mfma_f32_16x16x32_bf16 v[28:31], v[160:163], v[184:187], 0
	v_mfma_f32_16x16x32_bf16 v[24:27], v[168:171], v[184:187], 0
	v_mfma_f32_16x16x32_bf16 v[12:15], v[160:163], v[192:195], 0
	v_mfma_f32_16x16x32_bf16 v[8:11], v[168:171], v[192:195], 0
	v_mfma_f32_16x16x32_bf16 v[4:7], v[160:163], v[200:203], 0
	v_mfma_f32_16x16x32_bf16 v[0:3], v[168:171], v[200:203], 0
	v_mfma_f32_16x16x32_bf16 v[44:47], v[164:167], v[180:183], v[44:47]
	v_mfma_f32_16x16x32_bf16 v[40:43], v[172:175], v[180:183], v[40:43]
	v_mfma_f32_16x16x32_bf16 v[28:31], v[164:167], v[188:191], v[28:31]
	v_mfma_f32_16x16x32_bf16 v[24:27], v[172:175], v[188:191], v[24:27]
	v_mfma_f32_16x16x32_bf16 v[12:15], v[164:167], v[196:199], v[12:15]
	v_mfma_f32_16x16x32_bf16 v[8:11], v[172:175], v[196:199], v[8:11]
	v_mfma_f32_16x16x32_bf16 v[4:7], v[164:167], v[204:207], v[4:7]
	v_mfma_f32_16x16x32_bf16 v[0:3], v[172:175], v[204:207], v[0:3]
	s_barrier
	s_add_i32 s44, 0, 0x18000
	s_add_i32 s45, 0, 0x1c000
	ds_read_b128 v[144:147], v224
	ds_read_b128 v[148:151], v224 offset:1024
	ds_read_b128 v[152:155], v224 offset:2048
	ds_read_b128 v[156:159], v224 offset:3072
	ds_read_b128 v[160:163], v225
	ds_read_b128 v[164:167], v225 offset:1024
	ds_read_b128 v[168:171], v225 offset:2048
	ds_read_b128 v[172:175], v225 offset:3072
	s_add_u32 s22, s22, 0x80000
	s_addc_u32 s23, s23, 0
	s_mov_b32 m0, s93
	ds_read_b128 v[176:179], v143 offset:32768
	ds_read_b128 v[180:183], v143 offset:33792
	ds_read_b128 v[184:187], v143 offset:34816
	ds_read_b128 v[188:191], v143 offset:35840
	ds_read_b128 v[192:195], v143 offset:36864
	ds_read_b128 v[196:199], v143 offset:37888
	ds_read_b128 v[200:203], v143 offset:38912
	ds_read_b128 v[204:207], v143 offset:39936
	global_load_lds_dwordx4 v128, s[22:23]
	s_mov_b32 m0, s94
	s_nop 0
	global_load_lds_dwordx4 v132, s[22:23]
	s_waitcnt vmcnt(8)
	s_waitcnt lgkmcnt(0)
	s_barrier
	v_mfma_f32_16x16x32_bf16 v[124:127], v[144:147], v[176:179], v[124:127]
	v_mfma_f32_16x16x32_bf16 v[120:123], v[152:155], v[176:179], v[120:123]
	v_mfma_f32_16x16x32_bf16 v[116:119], v[144:147], v[184:187], v[116:119]
	v_mfma_f32_16x16x32_bf16 v[112:115], v[152:155], v[184:187], v[112:115]
	v_mfma_f32_16x16x32_bf16 v[100:103], v[144:147], v[192:195], v[100:103]
	v_mfma_f32_16x16x32_bf16 v[96:99], v[152:155], v[192:195], v[96:99]
	v_mfma_f32_16x16x32_bf16 v[84:87], v[144:147], v[200:203], v[84:87]
	v_mfma_f32_16x16x32_bf16 v[80:83], v[152:155], v[200:203], v[80:83]
	v_mfma_f32_16x16x32_bf16 v[124:127], v[148:151], v[180:183], v[124:127]
	v_mfma_f32_16x16x32_bf16 v[120:123], v[156:159], v[180:183], v[120:123]
	v_mfma_f32_16x16x32_bf16 v[116:119], v[148:151], v[188:191], v[116:119]
	v_mfma_f32_16x16x32_bf16 v[112:115], v[156:159], v[188:191], v[112:115]
	v_mfma_f32_16x16x32_bf16 v[100:103], v[148:151], v[196:199], v[100:103]
	v_mfma_f32_16x16x32_bf16 v[96:99], v[156:159], v[196:199], v[96:99]
	v_mfma_f32_16x16x32_bf16 v[84:87], v[148:151], v[204:207], v[84:87]
	v_mfma_f32_16x16x32_bf16 v[80:83], v[156:159], v[204:207], v[80:83]
	v_mfma_f32_16x16x32_bf16 v[108:111], v[160:163], v[176:179], v[108:111]
	v_mfma_f32_16x16x32_bf16 v[104:107], v[168:171], v[176:179], v[104:107]
	v_mfma_f32_16x16x32_bf16 v[92:95], v[160:163], v[184:187], v[92:95]
	v_mfma_f32_16x16x32_bf16 v[88:91], v[168:171], v[184:187], v[88:91]
	v_mfma_f32_16x16x32_bf16 v[76:79], v[160:163], v[192:195], v[76:79]
	v_mfma_f32_16x16x32_bf16 v[72:75], v[168:171], v[192:195], v[72:75]
	v_mfma_f32_16x16x32_bf16 v[68:71], v[160:163], v[200:203], v[68:71]
	v_mfma_f32_16x16x32_bf16 v[64:67], v[168:171], v[200:203], v[64:67]
	v_mfma_f32_16x16x32_bf16 v[108:111], v[164:167], v[180:183], v[108:111]
	v_mfma_f32_16x16x32_bf16 v[104:107], v[172:175], v[180:183], v[104:107]
	v_mfma_f32_16x16x32_bf16 v[92:95], v[164:167], v[188:191], v[92:95]
	v_mfma_f32_16x16x32_bf16 v[88:91], v[172:175], v[188:191], v[88:91]
	v_mfma_f32_16x16x32_bf16 v[76:79], v[164:167], v[196:199], v[76:79]
	v_mfma_f32_16x16x32_bf16 v[72:75], v[172:175], v[196:199], v[72:75]
	v_mfma_f32_16x16x32_bf16 v[68:71], v[164:167], v[204:207], v[68:71]
	v_mfma_f32_16x16x32_bf16 v[64:67], v[172:175], v[204:207], v[64:67]
	s_barrier
	s_add_i32 s22, s44, s96
	s_add_i32 m0, s22, 0xffffff80
	ds_read_b128 v[176:179], v143 offset:49152
	ds_read_b128 v[180:183], v143 offset:50176
	ds_read_b128 v[184:187], v143 offset:51200
	ds_read_b128 v[188:191], v143 offset:52224
	ds_read_b128 v[192:195], v143 offset:53248
	ds_read_b128 v[196:199], v143 offset:54272
	ds_read_b128 v[200:203], v143 offset:55296
	ds_read_b128 v[204:207], v143 offset:56320
	global_load_lds_dwordx4 v130, s[90:91] offset:128
	s_add_i32 m0, s22, 0x1f80
	s_add_u32 s22, s90, 0x80080
	s_addc_u32 s23, s91, 0
	s_add_i32 s44, s45, s96
	global_load_lds_dwordx4 v134, s[90:91] offset:128
	s_mov_b32 m0, s44
	s_nop 0
	global_load_lds_dwordx4 v130, s[22:23]
	s_add_i32 m0, s44, 0x2000
	s_nop 0
	global_load_lds_dwordx4 v134, s[22:23]
	s_add_u32 s22, s88, 0xfff80080
	s_addc_u32 s23, s89, -1
	s_cmp_eq_u32 s43, 28
	s_cselect_b32 s23, s30, s23
	s_cselect_b32 s22, s31, s22
	s_add_i32 m0, s92, 0xffffff80
	s_nop 0
	global_load_lds_dwordx4 v128, s[22:23] offset:128
	s_add_i32 m0, s6, 0xffffff80
	s_nop 0
	global_load_lds_dwordx4 v132, s[22:23] offset:128
	s_waitcnt vmcnt(8)
	s_waitcnt lgkmcnt(0)
	s_barrier
	v_mfma_f32_16x16x32_bf16 v[60:63], v[144:147], v[176:179], v[60:63]
	v_mfma_f32_16x16x32_bf16 v[56:59], v[152:155], v[176:179], v[56:59]
	v_mfma_f32_16x16x32_bf16 v[52:55], v[144:147], v[184:187], v[52:55]
	v_mfma_f32_16x16x32_bf16 v[48:51], v[152:155], v[184:187], v[48:51]
	v_mfma_f32_16x16x32_bf16 v[36:39], v[144:147], v[192:195], v[36:39]
	v_mfma_f32_16x16x32_bf16 v[32:35], v[152:155], v[192:195], v[32:35]
	v_mfma_f32_16x16x32_bf16 v[20:23], v[144:147], v[200:203], v[20:23]
	v_mfma_f32_16x16x32_bf16 v[16:19], v[152:155], v[200:203], v[16:19]
	v_mfma_f32_16x16x32_bf16 v[60:63], v[148:151], v[180:183], v[60:63]
	v_mfma_f32_16x16x32_bf16 v[56:59], v[156:159], v[180:183], v[56:59]
	v_mfma_f32_16x16x32_bf16 v[52:55], v[148:151], v[188:191], v[52:55]
	v_mfma_f32_16x16x32_bf16 v[48:51], v[156:159], v[188:191], v[48:51]
	v_mfma_f32_16x16x32_bf16 v[36:39], v[148:151], v[196:199], v[36:39]
	v_mfma_f32_16x16x32_bf16 v[32:35], v[156:159], v[196:199], v[32:35]
	v_mfma_f32_16x16x32_bf16 v[20:23], v[148:151], v[204:207], v[20:23]
	v_mfma_f32_16x16x32_bf16 v[16:19], v[156:159], v[204:207], v[16:19]
	v_mfma_f32_16x16x32_bf16 v[44:47], v[160:163], v[176:179], v[44:47]
	v_mfma_f32_16x16x32_bf16 v[40:43], v[168:171], v[176:179], v[40:43]
	v_mfma_f32_16x16x32_bf16 v[28:31], v[160:163], v[184:187], v[28:31]
	v_mfma_f32_16x16x32_bf16 v[24:27], v[168:171], v[184:187], v[24:27]
	v_mfma_f32_16x16x32_bf16 v[12:15], v[160:163], v[192:195], v[12:15]
	v_mfma_f32_16x16x32_bf16 v[8:11], v[168:171], v[192:195], v[8:11]
	v_mfma_f32_16x16x32_bf16 v[4:7], v[160:163], v[200:203], v[4:7]
	v_mfma_f32_16x16x32_bf16 v[0:3], v[168:171], v[200:203], v[0:3]
	v_mfma_f32_16x16x32_bf16 v[44:47], v[164:167], v[180:183], v[44:47]
	v_mfma_f32_16x16x32_bf16 v[40:43], v[172:175], v[180:183], v[40:43]
	v_mfma_f32_16x16x32_bf16 v[28:31], v[164:167], v[188:191], v[28:31]
	v_mfma_f32_16x16x32_bf16 v[24:27], v[172:175], v[188:191], v[24:27]
	v_mfma_f32_16x16x32_bf16 v[12:15], v[164:167], v[196:199], v[12:15]
	v_mfma_f32_16x16x32_bf16 v[8:11], v[172:175], v[196:199], v[8:11]
	v_mfma_f32_16x16x32_bf16 v[4:7], v[164:167], v[204:207], v[4:7]
	v_mfma_f32_16x16x32_bf16 v[0:3], v[172:175], v[204:207], v[0:3]
	s_barrier
	s_add_i32 s43, s43, 2
	s_add_u32 s88, s88, 0x100
	s_addc_u32 s89, s89, 0
	s_add_u32 s41, s41, 0x100
	s_addc_u32 s42, s42, 0
	s_cmp_gt_u32 s43, 29
	s_cbranch_scc0 .LBB0_631
